# S5 matrix build: D-term load issued with the task's other cold loads instead of mid-chain with an immediate wait
# speedup vs baseline: 1.0020x; 1.0020x over previous
; #define LAS __attribute__((address_space(3)))
; __device__ __forceinline__ void ssm_build(const Ptrs& P, int g, int part, LAS unsigned char* lds) {
;     ...
;     f32x2 cld[2], bld[2];
; #pragma unroll
;     for (int z = 0; z < 2; ++z) { const int e = tid + 512 * z; const int p = e >> 6, n = e & 63; cld[z] = (f32x2){P.c_re_()[((size_t)g * 16 + p) * 64 + n], P.c_im_()[((size_t)g * 16 + p) * 64 + n]};
;         bld[z] = (f32x2){P.b_re_()[(size_t)g * 1024 + e], P.b_im_()[(size_t)g * 1024 + e]}; }
;     LAS f32x2* coefl = (LAS f32x2*)(ktab + 16 * 4 * 16);
;     if (tid < 64) {
;         const int n = tid; const float step = expf(P.log_step_()[g]); const float lr = P.lam_re_()[g * 64 + n], li = P.lam_im_()[g * 64 + n];
;         const float mag1 = expf(lr * step); float s1, c1; sincosf(li * step, &s1, &c1); const float abr = mag1 * c1, abi = mag1 * s1;
;     ...
;             if (p == q) acc[0] += P.ssm_d_()[g * 16 + p];
.LBB0_16:
	s_load_dwordx2 s[98:99], s[0:1], 0x80
	s_ashr_i32 s10, s72, 2
	s_ashr_i32 s11, s10, 31
	s_lshl_b64 s[12:13], s[10:11], 10
	v_or_b32_e32 v10, s12, v1
	v_mov_b32_e32 v13, s13
	v_or_b32_e32 v12, v10, v95
	v_lshlrev_b64 v[12:13], 2, v[12:13]
	v_mov_b32_e32 v11, s13
	v_lshl_add_u64 v[14:15], s[64:65], 0, v[12:13]
	v_lshl_add_u64 v[12:13], s[66:67], 0, v[12:13]
	global_load_dword v17, v[12:13], off
	v_mov_b32_e32 v13, s13
	v_or_b32_e32 v12, s12, v0
	v_lshl_add_u64 v[10:11], v[10:11], 0, v[68:69]
	v_lshlrev_b64 v[12:13], 2, v[12:13]
	v_lshlrev_b64 v[10:11], 2, v[10:11]
	global_load_dword v16, v[14:15], off
	v_lshl_add_u64 v[18:19], s[60:61], 0, v[12:13]
	v_lshl_add_u64 v[12:13], s[62:63], 0, v[12:13]
	v_lshl_add_u64 v[14:15], s[64:65], 0, v[10:11]
	v_lshl_add_u64 v[10:11], s[66:67], 0, v[10:11]
	global_load_dword v20, v[14:15], off
	global_load_dword v21, v[10:11], off
	s_nop 0
	global_load_dword v14, v[18:19], off
	global_load_dword v10, v[18:19], off offset:2048
	s_nop 0
	global_load_dword v18, v[12:13], off
	s_nop 0
	global_load_dword v12, v[12:13], off offset:2048
	s_and_b32 s18, s72, 3
	v_lshl_or_b32 v122, s10, 4, v100
	v_ashrrev_i32_e32 v123, 31, v122
	s_waitcnt lgkmcnt(0)
	v_lshl_add_u64 v[122:123], v[122:123], 2, s[98:99]
	global_load_dword v124, v[122:123], off
	s_and_saveexec_b64 s[12:13], s[4:5]
	s_cbranch_execz .LBB0_26
	s_lshl_b64 s[14:15], s[10:11], 2
	s_add_u32 s14, s58, s14
	s_addc_u32 s15, s59, s15
	global_load_dword v2, v3, s[14:15]
	v_lshl_or_b32 v22, s10, 6, v0
	v_ashrrev_i32_e32 v23, 31, v22
	v_lshlrev_b64 v[24:25], 2, v[22:23]
	v_lshl_add_u64 v[22:23], s[56:57], 0, v[24:25]
	global_load_dword v23, v[22:23], off
	v_lshl_add_u64 v[24:25], s[54:55], 0, v[24:25]
	global_load_dword v22, v[24:25], off
	s_brev_b32 s14, 18
	s_waitcnt vmcnt(2)
	v_mul_f32_e32 v11, 0x3fb8aa3b, v2
	v_fma_f32 v13, v2, s31, -v11
	v_rndne_f32_e32 v15, v11
	v_fmac_f32_e32 v13, 0x32a5705f, v2
	v_sub_f32_e32 v11, v11, v15
	v_add_f32_e32 v11, v11, v13
	v_cvt_i32_f32_e32 v15, v15
	v_exp_f32_e32 v11, v11
	v_cmp_ngt_f32_e32 vcc, s33, v2
	v_ldexp_f32 v11, v11, v15
	s_nop 0
	v_cndmask_b32_e32 v11, 0, v11, vcc
	v_cmp_nlt_f32_e32 vcc, s68, v2
	s_nop 1
	v_cndmask_b32_e32 v15, v57, v11, vcc
	s_waitcnt vmcnt(1)
	v_mul_f32_e32 v11, v15, v23
	v_and_b32_e32 v13, 0x7fffffff, v11
	v_cmp_nlt_f32_e64 s[14:15], |v11|, s14
	s_and_saveexec_b64 s[16:17], s[14:15]
	s_xor_b64 s[14:15], exec, s[16:17]
	s_cbranch_execz .LBB0_19
	v_lshrrev_b32_e32 v2, 23, v13
	v_add_u32_e32 v2, 0xffffff88, v2
	v_cmp_lt_u32_e32 vcc, 63, v2
	s_mov_b32 s19, 0xfe5163ab
	s_nop 0
	v_cndmask_b32_e32 v19, 0, v58, vcc
	v_add_u32_e32 v2, v19, v2
	v_cmp_lt_u32_e64 s[16:17], 31, v2
	s_nop 1
	v_cndmask_b32_e64 v19, 0, v59, s[16:17]
	v_add_u32_e32 v2, v19, v2
	v_cmp_lt_u32_e64 s[20:21], 31, v2
	s_nop 1
	v_cndmask_b32_e64 v19, 0, v59, s[20:21]
	v_add_u32_e32 v19, v19, v2
	v_and_b32_e32 v2, 0x7fffff, v13
	v_or_b32_e32 v36, 0x800000, v2
	v_mad_u64_u32 v[24:25], s[22:23], v36, s19, 0
	v_mov_b32_e32 v2, v25
	s_mov_b32 s19, 0x3c439041
	v_mad_u64_u32 v[26:27], s[22:23], v36, s19, v[2:3]
	v_mov_b32_e32 v2, v27
	s_mov_b32 s19, 0xdb629599
	v_mad_u64_u32 v[28:29], s[22:23], v36, s19, v[2:3]
	v_mov_b32_e32 v2, v29
	s_mov_b32 s19, 0xf534ddc0
	v_mad_u64_u32 v[30:31], s[22:23], v36, s19, v[2:3]
	v_mov_b32_e32 v2, v31
	s_mov_b32 s19, 0xfc2757d1
	v_mad_u64_u32 v[32:33], s[22:23], v36, s19, v[2:3]
	v_mov_b32_e32 v2, v33
	s_mov_b32 s19, 0x4e441529
	v_mad_u64_u32 v[34:35], s[22:23], v36, s19, v[2:3]
	v_mov_b32_e32 v2, v35
	s_mov_b32 s19, 0xa2f9836e
	v_mad_u64_u32 v[36:37], s[22:23], v36, s19, v[2:3]
	v_cndmask_b32_e32 v25, v34, v30, vcc
	v_cndmask_b32_e32 v2, v36, v32, vcc
	v_cndmask_b32_e32 v29, v37, v34, vcc
	v_cndmask_b32_e64 v27, v2, v25, s[16:17]
	v_cndmask_b32_e64 v2, v29, v2, s[16:17]
	v_cndmask_b32_e32 v29, v32, v28, vcc
	v_cndmask_b32_e64 v25, v25, v29, s[16:17]
	v_cndmask_b32_e64 v2, v2, v27, s[20:21]
	v_cndmask_b32_e64 v27, v27, v25, s[20:21]
	v_sub_u32_e32 v31, 32, v19
	v_alignbit_b32 v32, v2, v27, v31
	v_cmp_eq_u32_e64 s[22:23], 0, v19
	v_cndmask_b32_e32 v24, v28, v24, vcc
	s_nop 0
	v_cndmask_b32_e64 v19, v32, v2, s[22:23]
	v_cndmask_b32_e32 v2, v30, v26, vcc
	v_cndmask_b32_e64 v26, v29, v2, s[16:17]
	v_cndmask_b32_e64 v25, v25, v26, s[20:21]
	v_alignbit_b32 v29, v27, v25, v31
	v_cndmask_b32_e64 v27, v29, v27, s[22:23]
	v_bfe_u32 v32, v19, 29, 1
	v_cndmask_b32_e64 v2, v2, v24, s[16:17]
	v_alignbit_b32 v29, v19, v27, 30
	v_sub_u32_e32 v33, 0, v32
	v_cndmask_b32_e64 v2, v26, v2, s[20:21]
	v_xor_b32_e32 v29, v29, v33
	v_alignbit_b32 v24, v25, v2, v31
	v_cndmask_b32_e64 v24, v24, v25, s[22:23]
	v_ffbh_u32_e32 v26, v29
	v_alignbit_b32 v25, v27, v24, 30
	v_min_u32_e32 v26, 32, v26
	v_alignbit_b32 v2, v24, v2, 30
	v_xor_b32_e32 v25, v25, v33
	v_sub_u32_e32 v27, 31, v26
	v_xor_b32_e32 v2, v2, v33
	v_alignbit_b32 v28, v29, v25, v27
	v_alignbit_b32 v2, v25, v2, v27
	v_alignbit_b32 v24, v28, v2, 9
	v_ffbh_u32_e32 v25, v24
	v_min_u32_e32 v25, 32, v25
	v_lshrrev_b32_e32 v30, 29, v19
	v_not_b32_e32 v27, v25
	v_alignbit_b32 v2, v24, v2, v27
	v_lshlrev_b32_e32 v24, 31, v30
	v_or_b32_e32 v27, 0x33000000, v24
	v_add_lshl_u32 v25, v25, v26, 23
	v_lshrrev_b32_e32 v2, 9, v2
	v_sub_u32_e32 v25, v27, v25
	v_or_b32_e32 v24, 0.5, v24
	v_lshlrev_b32_e32 v26, 23, v26
	v_or_b32_e32 v2, v25, v2
	v_lshrrev_b32_e32 v25, 9, v28
	v_sub_u32_e32 v24, v24, v26
	v_or_b32_e32 v24, v25, v24
	v_mul_f32_e32 v25, 0x3fc90fda, v24
	s_mov_b32 s16, 0x3fc90fda
	v_fma_f32 v26, v24, s16, -v25
	v_fmac_f32_e32 v26, 0x33a22168, v24
	v_fmac_f32_e32 v26, 0x3fc90fda, v2
	v_lshrrev_b32_e32 v19, 30, v19
	v_add_f32_e32 v2, v25, v26
	v_add_u32_e32 v19, v32, v19

; __device__ __forceinline__ void ssm_build(const Ptrs& P, int g, int part, LAS unsigned char* lds) {
;     ...
; #pragma unroll 1
;         for (int nn = 0; nn < 8; ++nn) { const int n = sl * 8 + nn; const f32x2 c = cc[p * 64 + n], b = bb[n * 16 + q]; const float gr = c.x * b.x - c.y * b.y, gi = c.x * b.y + c.y * b.x;
; #pragma unroll
;             for (int k = 0; k < 16; ++k) { const f32x2 a = apw[k * 64 + n]; acc[k] += gr * a.x - gi * a.y; } }
; #pragma unroll
;         for (int k = 0; k < 16; ++k) { float v = acc[k]; v += __shfl_xor(v, 1); v += __shfl_xor(v, 2); v += __shfl_xor(v, 4); acc[k] = v; }
;         if (sl == 0) {
;             if (p == q) acc[0] += P.ssm_d_()[g * 16 + p];
.LBB0_31:
	v_add_u32_e32 v27, s12, v2
	ds_read_b64 v[92:93], v26
	v_add_u32_e32 v71, s12, v51
	ds_read_b64 v[104:105], v27
	ds_read2st64_b64 v[28:31], v71 offset1:1
	ds_read2st64_b64 v[32:35], v71 offset0:2 offset1:3
	ds_read2st64_b64 v[36:39], v71 offset0:4 offset1:5
	ds_read2st64_b64 v[40:43], v71 offset0:6 offset1:7
	ds_read2st64_b64 v[44:47], v71 offset0:8 offset1:9
	ds_read2st64_b64 v[62:65], v71 offset0:10 offset1:11
	ds_read2st64_b64 v[84:87], v71 offset0:12 offset1:13
	ds_read2st64_b64 v[88:91], v71 offset0:14 offset1:15
	s_add_i32 s12, s12, 8
	v_add_u32_e32 v26, 0x80, v26
	s_waitcnt lgkmcnt(8)
	v_pk_mul_f32 v[106:107], v[104:105], v[92:93]
	v_pk_mul_f32 v[92:93], v[104:105], v[92:93] op_sel:[0,1] op_sel_hi:[1,0]
	s_waitcnt lgkmcnt(7)
	v_mov_b32_e32 v105, v30
	v_mov_b32_e32 v30, v29
	s_waitcnt lgkmcnt(6)
	v_mov_b32_e32 v29, v34
	v_mov_b32_e32 v34, v33
	s_waitcnt lgkmcnt(5)
	v_mov_b32_e32 v33, v38
	v_mov_b32_e32 v38, v37
	s_waitcnt lgkmcnt(4)
	v_mov_b32_e32 v37, v42
	v_mov_b32_e32 v42, v41
	s_waitcnt lgkmcnt(3)
	v_mov_b32_e32 v41, v46
	v_mov_b32_e32 v46, v45
	s_waitcnt lgkmcnt(2)
	v_mov_b32_e32 v45, v64
	v_mov_b32_e32 v64, v63
	s_waitcnt lgkmcnt(1)
	v_mov_b32_e32 v63, v86
	v_mov_b32_e32 v86, v85
	s_waitcnt lgkmcnt(0)
	v_mov_b32_e32 v85, v90
	v_mov_b32_e32 v90, v89
	v_pk_add_f32 v[92:93], v[92:93], v[92:93] op_sel:[0,1] op_sel_hi:[0,1]
	v_mov_b32_e32 v104, v28
	v_mov_b32_e32 v28, v32
	v_mov_b32_e32 v32, v36
	v_mov_b32_e32 v36, v40
	v_mov_b32_e32 v40, v44
	v_mov_b32_e32 v44, v62
	v_mov_b32_e32 v62, v84
	v_mov_b32_e32 v84, v88
	v_pk_add_f32 v[88:89], v[106:107], v[106:107] op_sel:[0,1] op_sel_hi:[0,1] neg_lo:[0,1] neg_hi:[0,1]
	v_pk_mul_f32 v[30:31], v[30:31], v[92:93]
	v_pk_mul_f32 v[34:35], v[92:93], v[34:35]
	v_pk_mul_f32 v[38:39], v[92:93], v[38:39]
	v_pk_mul_f32 v[42:43], v[92:93], v[42:43]
	v_pk_mul_f32 v[46:47], v[92:93], v[46:47]
	v_pk_mul_f32 v[64:65], v[92:93], v[64:65]
	v_pk_mul_f32 v[86:87], v[92:93], v[86:87]
	v_pk_mul_f32 v[90:91], v[92:93], v[90:91]
	v_pk_fma_f32 v[30:31], v[104:105], v[88:89], v[30:31] neg_lo:[0,0,1] neg_hi:[0,0,1]
	v_pk_fma_f32 v[28:29], v[88:89], v[28:29], v[34:35] neg_lo:[0,0,1] neg_hi:[0,0,1]
	v_pk_fma_f32 v[32:33], v[88:89], v[32:33], v[38:39] neg_lo:[0,0,1] neg_hi:[0,0,1]
	v_pk_fma_f32 v[34:35], v[88:89], v[36:37], v[42:43] neg_lo:[0,0,1] neg_hi:[0,0,1]
	v_pk_fma_f32 v[36:37], v[88:89], v[40:41], v[46:47] neg_lo:[0,0,1] neg_hi:[0,0,1]
	v_pk_fma_f32 v[38:39], v[88:89], v[44:45], v[64:65] neg_lo:[0,0,1] neg_hi:[0,0,1]
	v_pk_fma_f32 v[40:41], v[88:89], v[62:63], v[86:87] neg_lo:[0,0,1] neg_hi:[0,0,1]
	v_pk_fma_f32 v[42:43], v[88:89], v[84:85], v[90:91] neg_lo:[0,0,1] neg_hi:[0,0,1]
	s_cmp_eq_u32 s12, 64
	v_pk_add_f32 v[24:25], v[24:25], v[30:31]
	v_pk_add_f32 v[22:23], v[22:23], v[28:29]
	v_pk_add_f32 v[20:21], v[20:21], v[32:33]
	v_pk_add_f32 v[18:19], v[18:19], v[34:35]
	v_pk_add_f32 v[16:17], v[16:17], v[36:37]
	v_pk_add_f32 v[14:15], v[14:15], v[38:39]
	v_pk_add_f32 v[12:13], v[12:13], v[40:41]
	v_pk_add_f32 v[10:11], v[10:11], v[42:43]
	s_cbranch_scc0 .LBB0_31
	ds_bpermute_b32 v28, v48, v22
	ds_bpermute_b32 v29, v48, v23
	ds_bpermute_b32 v30, v48, v20
	ds_bpermute_b32 v31, v48, v21
	ds_bpermute_b32 v38, v48, v14
	ds_bpermute_b32 v39, v48, v15
	s_waitcnt lgkmcnt(4)
	v_pk_add_f32 v[28:29], v[22:23], v[28:29]
	ds_bpermute_b32 v32, v49, v28
	s_waitcnt lgkmcnt(3)
	v_pk_add_f32 v[30:31], v[20:21], v[30:31]
	ds_bpermute_b32 v33, v49, v29
	ds_bpermute_b32 v34, v49, v30
	ds_bpermute_b32 v35, v49, v31
	s_waitcnt lgkmcnt(4)
	v_pk_add_f32 v[14:15], v[14:15], v[38:39]
	ds_bpermute_b32 v26, v48, v24
	s_waitcnt lgkmcnt(3)
	v_pk_add_f32 v[20:21], v[28:29], v[32:33]
	ds_bpermute_b32 v32, v48, v18
	s_waitcnt lgkmcnt(2)
	v_pk_add_f32 v[28:29], v[30:31], v[34:35]
	ds_bpermute_b32 v33, v48, v19
	ds_bpermute_b32 v34, v48, v16
	ds_bpermute_b32 v35, v48, v17
	ds_bpermute_b32 v27, v48, v25
	ds_bpermute_b32 v40, v48, v12
	s_waitcnt lgkmcnt(4)
	v_pk_add_f32 v[18:19], v[18:19], v[32:33]
	ds_bpermute_b32 v32, v49, v18
	s_waitcnt lgkmcnt(3)
	v_pk_add_f32 v[34:35], v[16:17], v[34:35]
	ds_bpermute_b32 v33, v49, v19
	ds_bpermute_b32 v36, v49, v34
	ds_bpermute_b32 v37, v49, v35
	ds_bpermute_b32 v41, v48, v13
	s_waitcnt lgkmcnt(6)
	v_pk_add_f32 v[24:25], v[24:25], v[26:27]
	s_waitcnt lgkmcnt(3)
	v_pk_add_f32 v[16:17], v[18:19], v[32:33]
	ds_bpermute_b32 v26, v49, v24
	s_waitcnt lgkmcnt(2)
	v_pk_add_f32 v[18:19], v[34:35], v[36:37]
	ds_bpermute_b32 v36, v49, v14
	ds_bpermute_b32 v37, v49, v15
	s_waitcnt lgkmcnt(3)
	v_pk_add_f32 v[12:13], v[12:13], v[40:41]
	ds_bpermute_b32 v27, v49, v25
	ds_bpermute_b32 v40, v49, v12
	ds_bpermute_b32 v41, v49, v13
	s_waitcnt lgkmcnt(3)
	v_pk_add_f32 v[36:37], v[14:15], v[36:37]
	ds_bpermute_b32 v14, v48, v10
	ds_bpermute_b32 v15, v48, v11
	s_waitcnt lgkmcnt(4)
	v_pk_add_f32 v[22:23], v[24:25], v[26:27]
	s_waitcnt lgkmcnt(2)
	v_pk_add_f32 v[40:41], v[12:13], v[40:41]
	ds_bpermute_b32 v24, v50, v22
	ds_bpermute_b32 v25, v50, v23
	s_waitcnt lgkmcnt(2)
	v_pk_add_f32 v[10:11], v[10:11], v[14:15]
	ds_bpermute_b32 v14, v49, v10
	ds_bpermute_b32 v15, v49, v11
	ds_bpermute_b32 v26, v50, v20
	ds_bpermute_b32 v27, v50, v21
	ds_bpermute_b32 v30, v50, v28
	ds_bpermute_b32 v31, v50, v29
	s_waitcnt lgkmcnt(4)
	v_pk_add_f32 v[44:45], v[10:11], v[14:15]
	ds_bpermute_b32 v32, v50, v16
	ds_bpermute_b32 v33, v50, v17
	ds_bpermute_b32 v34, v50, v18
	ds_bpermute_b32 v35, v50, v19
	ds_bpermute_b32 v38, v50, v36
	ds_bpermute_b32 v39, v50, v37
	ds_bpermute_b32 v42, v50, v40
	ds_bpermute_b32 v43, v50, v41
	ds_bpermute_b32 v46, v50, v44
	ds_bpermute_b32 v47, v50, v45
	s_lshl_b32 s23, s18, 2
	s_and_saveexec_b64 s[12:13], s[6:7]
	s_cbranch_execz .LBB0_36
	v_add_u32_e32 v2, s23, v99
	v_pk_add_f32 v[10:11], v[22:23], v[24:25]
	s_waitcnt lgkmcnt(12)
	v_pk_add_f32 v[12:13], v[20:21], v[26:27]
	s_waitcnt lgkmcnt(10)
	v_pk_add_f32 v[14:15], v[28:29], v[30:31]
	s_waitcnt lgkmcnt(8)
	v_pk_add_f32 v[16:17], v[16:17], v[32:33]
	s_waitcnt lgkmcnt(6)
	v_pk_add_f32 v[18:19], v[18:19], v[34:35]
	s_waitcnt lgkmcnt(4)
	v_pk_add_f32 v[20:21], v[36:37], v[38:39]
	s_waitcnt lgkmcnt(2)
	v_pk_add_f32 v[22:23], v[40:41], v[42:43]
	s_waitcnt lgkmcnt(0)
	v_pk_add_f32 v[24:25], v[44:45], v[46:47]
	v_cmp_eq_u32_e32 vcc, v2, v100
	s_and_saveexec_b64 s[14:15], vcc
	s_cbranch_execz .LBB0_35
	s_waitcnt vmcnt(0)
	v_add_f32_e32 v10, v10, v124

; #define LAS __attribute__((address_space(3)))
; __device__ __forceinline__ void ssm_build(const Ptrs& P, int g, int part, LAS unsigned char* lds) {
;     ...
;     f32x2 cld[2], bld[2];
; #pragma unroll
;     for (int z = 0; z < 2; ++z) { const int e = tid + 512 * z; const int p = e >> 6, n = e & 63; cld[z] = (f32x2){P.c_re_()[((size_t)g * 16 + p) * 64 + n], P.c_im_()[((size_t)g * 16 + p) * 64 + n]};
;         bld[z] = (f32x2){P.b_re_()[(size_t)g * 1024 + e], P.b_im_()[(size_t)g * 1024 + e]}; }
;     LAS f32x2* coefl = (LAS f32x2*)(ktab + 16 * 4 * 16);
;     if (tid < 64) {
;         const int n = tid; const float step = expf(P.log_step_()[g]); const float lr = P.lam_re_()[g * 64 + n], li = P.lam_im_()[g * 64 + n];
;         const float mag1 = expf(lr * step); float s1, c1; sincosf(li * step, &s1, &c1); const float abr = mag1 * c1, abi = mag1 * s1;
;     ...
;             if (p == q) acc[0] += P.ssm_d_()[g * 16 + p];
.LBB0_123:
	s_ashr_i32 s10, s71, 2
	s_ashr_i32 s11, s10, 31
	s_lshl_b64 s[0:1], s[10:11], 10
	v_or_b32_e32 v8, s0, v1
	v_mov_b32_e32 v11, s1
	v_or_b32_e32 v10, v8, v95
	v_lshlrev_b64 v[10:11], 2, v[10:11]
	v_mov_b32_e32 v9, s1
	v_lshl_add_u64 v[12:13], s[64:65], 0, v[10:11]
	v_lshl_add_u64 v[10:11], s[66:67], 0, v[10:11]
	global_load_dword v15, v[10:11], off
	v_mov_b32_e32 v11, s1
	v_or_b32_e32 v10, s0, v0
	v_lshl_add_u64 v[8:9], v[8:9], 0, v[68:69]
	v_lshlrev_b64 v[10:11], 2, v[10:11]
	v_lshlrev_b64 v[8:9], 2, v[8:9]
	global_load_dword v14, v[12:13], off
	v_lshl_add_u64 v[16:17], s[60:61], 0, v[10:11]
	v_lshl_add_u64 v[10:11], s[62:63], 0, v[10:11]
	v_lshl_add_u64 v[12:13], s[64:65], 0, v[8:9]
	v_lshl_add_u64 v[8:9], s[66:67], 0, v[8:9]
	global_load_dword v18, v[12:13], off
	global_load_dword v19, v[8:9], off
	s_nop 0
	global_load_dword v12, v[16:17], off
	global_load_dword v8, v[16:17], off offset:2048
	s_nop 0
	global_load_dword v16, v[10:11], off
	s_nop 0
	global_load_dword v10, v[10:11], off offset:2048
	s_and_b32 s18, s71, 3
	v_readlane_b32 s98, v244, 2
	v_readlane_b32 s99, v244, 3
	v_lshl_or_b32 v122, s10, 4, v100
	v_ashrrev_i32_e32 v123, 31, v122
	s_nop 1
	v_lshl_add_u64 v[122:123], v[122:123], 2, s[98:99]
	global_load_dword v124, v[122:123], off
	s_and_saveexec_b64 s[12:13], s[4:5]
	s_cbranch_execz .LBB0_133
	s_lshl_b64 s[0:1], s[10:11], 2
	s_add_u32 s0, s58, s0
	s_addc_u32 s1, s59, s1
	global_load_dword v2, v3, s[0:1]
	v_lshl_or_b32 v20, s10, 6, v0
	v_ashrrev_i32_e32 v21, 31, v20
	v_lshlrev_b64 v[22:23], 2, v[20:21]
	v_lshl_add_u64 v[20:21], s[56:57], 0, v[22:23]
	global_load_dword v21, v[20:21], off
	v_lshl_add_u64 v[22:23], s[54:55], 0, v[22:23]
	global_load_dword v20, v[22:23], off
	s_brev_b32 s0, 18
	s_waitcnt vmcnt(2)
	v_mul_f32_e32 v9, 0x3fb8aa3b, v2
	v_fma_f32 v11, v2, s3, -v9
	v_rndne_f32_e32 v13, v9
	v_fmac_f32_e32 v11, 0x32a5705f, v2
	v_sub_f32_e32 v9, v9, v13
	v_add_f32_e32 v9, v9, v11
	v_cvt_i32_f32_e32 v13, v13
	v_exp_f32_e32 v9, v9
	v_cmp_ngt_f32_e32 vcc, s22, v2
	v_ldexp_f32 v9, v9, v13
	s_nop 0
	v_cndmask_b32_e32 v9, 0, v9, vcc
	v_cmp_nlt_f32_e32 vcc, s23, v2
	s_nop 1
	v_cndmask_b32_e32 v13, v56, v9, vcc
	s_waitcnt vmcnt(1)
	v_mul_f32_e32 v9, v13, v21
	v_and_b32_e32 v11, 0x7fffffff, v9
	v_cmp_nlt_f32_e64 s[0:1], |v9|, s0
	s_and_saveexec_b64 s[14:15], s[0:1]
	s_xor_b64 s[14:15], exec, s[14:15]
	s_cbranch_execz .LBB0_126
	v_lshrrev_b32_e32 v2, 23, v11
	v_add_u32_e32 v2, 0xffffff88, v2
	v_cmp_lt_u32_e32 vcc, 63, v2
	s_mov_b32 s19, 0xfe5163ab
	s_nop 0
	v_cndmask_b32_e32 v17, 0, v57, vcc
	v_add_u32_e32 v2, v17, v2
	v_cmp_lt_u32_e64 s[0:1], 31, v2
	s_nop 1
	v_cndmask_b32_e64 v17, 0, v58, s[0:1]
	v_add_u32_e32 v2, v17, v2
	v_cmp_lt_u32_e64 s[16:17], 31, v2
	s_nop 1
	v_cndmask_b32_e64 v17, 0, v58, s[16:17]
	v_add_u32_e32 v17, v17, v2
	v_and_b32_e32 v2, 0x7fffff, v11
	v_or_b32_e32 v34, 0x800000, v2
	v_mad_u64_u32 v[22:23], s[20:21], v34, s19, 0
	v_mov_b32_e32 v2, v23
	s_mov_b32 s19, 0x3c439041
	v_mad_u64_u32 v[24:25], s[20:21], v34, s19, v[2:3]
	v_mov_b32_e32 v2, v25
	s_mov_b32 s19, 0xdb629599
	v_mad_u64_u32 v[26:27], s[20:21], v34, s19, v[2:3]
	v_mov_b32_e32 v2, v27
	s_mov_b32 s19, 0xf534ddc0
	v_mad_u64_u32 v[28:29], s[20:21], v34, s19, v[2:3]
	v_mov_b32_e32 v2, v29
	s_mov_b32 s19, 0xfc2757d1
	v_mad_u64_u32 v[30:31], s[20:21], v34, s19, v[2:3]
	v_mov_b32_e32 v2, v31
	s_mov_b32 s19, 0x4e441529
	v_mad_u64_u32 v[32:33], s[20:21], v34, s19, v[2:3]
	v_mov_b32_e32 v2, v33
	s_mov_b32 s19, 0xa2f9836e
	v_mad_u64_u32 v[34:35], s[20:21], v34, s19, v[2:3]
	v_cndmask_b32_e32 v23, v32, v28, vcc
	v_cndmask_b32_e32 v2, v34, v30, vcc
	v_cndmask_b32_e32 v27, v35, v32, vcc
	v_cndmask_b32_e64 v25, v2, v23, s[0:1]
	v_cndmask_b32_e64 v2, v27, v2, s[0:1]
	v_cndmask_b32_e32 v27, v30, v26, vcc
	v_cndmask_b32_e64 v23, v23, v27, s[0:1]
	v_cndmask_b32_e64 v2, v2, v25, s[16:17]
	v_cndmask_b32_e64 v25, v25, v23, s[16:17]
	v_sub_u32_e32 v29, 32, v17
	v_alignbit_b32 v30, v2, v25, v29
	v_cmp_eq_u32_e64 s[20:21], 0, v17
	v_cndmask_b32_e32 v22, v26, v22, vcc
	s_nop 0
	v_cndmask_b32_e64 v17, v30, v2, s[20:21]
	v_cndmask_b32_e32 v2, v28, v24, vcc
	v_cndmask_b32_e64 v24, v27, v2, s[0:1]
	v_cndmask_b32_e64 v23, v23, v24, s[16:17]
	v_alignbit_b32 v27, v25, v23, v29
	v_cndmask_b32_e64 v25, v27, v25, s[20:21]
	v_bfe_u32 v30, v17, 29, 1
	v_cndmask_b32_e64 v2, v2, v22, s[0:1]
	v_alignbit_b32 v27, v17, v25, 30
	v_sub_u32_e32 v31, 0, v30
	v_cndmask_b32_e64 v2, v24, v2, s[16:17]
	v_xor_b32_e32 v27, v27, v31
	v_alignbit_b32 v22, v23, v2, v29
	v_cndmask_b32_e64 v22, v22, v23, s[20:21]
	v_ffbh_u32_e32 v24, v27
	v_alignbit_b32 v23, v25, v22, 30
	v_min_u32_e32 v24, 32, v24
	v_alignbit_b32 v2, v22, v2, 30
	v_xor_b32_e32 v23, v23, v31
	v_sub_u32_e32 v25, 31, v24
	v_xor_b32_e32 v2, v2, v31
	v_alignbit_b32 v26, v27, v23, v25
	v_alignbit_b32 v2, v23, v2, v25
	v_alignbit_b32 v22, v26, v2, 9
	v_ffbh_u32_e32 v23, v22
	v_min_u32_e32 v23, 32, v23
	v_lshrrev_b32_e32 v28, 29, v17
	v_not_b32_e32 v25, v23
	v_alignbit_b32 v2, v22, v2, v25
	v_lshlrev_b32_e32 v22, 31, v28
	v_or_b32_e32 v25, 0x33000000, v22
	v_add_lshl_u32 v23, v23, v24, 23
	v_lshrrev_b32_e32 v2, 9, v2
	v_sub_u32_e32 v23, v25, v23
	v_or_b32_e32 v22, 0.5, v22
	v_lshlrev_b32_e32 v24, 23, v24
	v_or_b32_e32 v2, v23, v2
	v_lshrrev_b32_e32 v23, 9, v26
	v_sub_u32_e32 v22, v22, v24
	v_or_b32_e32 v22, v23, v22
	v_mul_f32_e32 v23, 0x3fc90fda, v22
	s_mov_b32 s0, 0x3fc90fda
	v_fma_f32 v24, v22, s0, -v23
	v_fmac_f32_e32 v24, 0x33a22168, v22
	v_fmac_f32_e32 v24, 0x3fc90fda, v2
	v_lshrrev_b32_e32 v17, 30, v17
	v_add_f32_e32 v2, v23, v24
	v_add_u32_e32 v17, v30, v17

; __device__ __forceinline__ void ssm_build(const Ptrs& P, int g, int part, LAS unsigned char* lds) {
;     ...
; #pragma unroll 1
;         for (int nn = 0; nn < 8; ++nn) { const int n = sl * 8 + nn; const f32x2 c = cc[p * 64 + n], b = bb[n * 16 + q]; const float gr = c.x * b.x - c.y * b.y, gi = c.x * b.y + c.y * b.x;
; #pragma unroll
;             for (int k = 0; k < 16; ++k) { const f32x2 a = apw[k * 64 + n]; acc[k] += gr * a.x - gi * a.y; } }
; #pragma unroll
;         for (int k = 0; k < 16; ++k) { float v = acc[k]; v += __shfl_xor(v, 1); v += __shfl_xor(v, 2); v += __shfl_xor(v, 4); acc[k] = v; }
;         if (sl == 0) {
;             if (p == q) acc[0] += P.ssm_d_()[g * 16 + p];
.LBB0_138:
	v_add_u32_e32 v25, s0, v2
	ds_read_b64 v[92:93], v24
	v_add_u32_e32 v61, s0, v50
	ds_read_b64 v[104:105], v25
	ds_read2st64_b64 v[26:29], v61 offset1:1
	ds_read2st64_b64 v[30:33], v61 offset0:2 offset1:3
	ds_read2st64_b64 v[34:37], v61 offset0:4 offset1:5
	ds_read2st64_b64 v[38:41], v61 offset0:6 offset1:7
	ds_read2st64_b64 v[42:45], v61 offset0:8 offset1:9
	ds_read2st64_b64 v[62:65], v61 offset0:10 offset1:11
	ds_read2st64_b64 v[84:87], v61 offset0:12 offset1:13
	ds_read2st64_b64 v[88:91], v61 offset0:14 offset1:15
	s_add_i32 s0, s0, 8
	v_add_u32_e32 v24, 0x80, v24
	s_waitcnt lgkmcnt(8)
	v_pk_mul_f32 v[106:107], v[104:105], v[92:93]
	v_pk_mul_f32 v[92:93], v[104:105], v[92:93] op_sel:[0,1] op_sel_hi:[1,0]
	s_waitcnt lgkmcnt(7)
	v_mov_b32_e32 v105, v28
	v_mov_b32_e32 v28, v27
	s_waitcnt lgkmcnt(6)
	v_mov_b32_e32 v27, v32
	v_mov_b32_e32 v32, v31
	s_waitcnt lgkmcnt(5)
	v_mov_b32_e32 v31, v36
	v_mov_b32_e32 v36, v35
	s_waitcnt lgkmcnt(4)
	v_mov_b32_e32 v35, v40
	v_mov_b32_e32 v40, v39
	s_waitcnt lgkmcnt(3)
	v_mov_b32_e32 v39, v44
	v_mov_b32_e32 v44, v43
	s_waitcnt lgkmcnt(2)
	v_mov_b32_e32 v43, v64
	v_mov_b32_e32 v64, v63
	s_waitcnt lgkmcnt(1)
	v_mov_b32_e32 v63, v86
	v_mov_b32_e32 v86, v85
	s_waitcnt lgkmcnt(0)
	v_mov_b32_e32 v85, v90
	v_mov_b32_e32 v90, v89
	v_pk_add_f32 v[92:93], v[92:93], v[92:93] op_sel:[0,1] op_sel_hi:[0,1]
	v_mov_b32_e32 v104, v26
	v_mov_b32_e32 v26, v30
	v_mov_b32_e32 v30, v34
	v_mov_b32_e32 v34, v38
	v_mov_b32_e32 v38, v42
	v_mov_b32_e32 v42, v62
	v_mov_b32_e32 v62, v84
	v_mov_b32_e32 v84, v88
	v_pk_add_f32 v[88:89], v[106:107], v[106:107] op_sel:[0,1] op_sel_hi:[0,1] neg_lo:[0,1] neg_hi:[0,1]
	v_pk_mul_f32 v[28:29], v[28:29], v[92:93]
	v_pk_mul_f32 v[32:33], v[92:93], v[32:33]
	v_pk_mul_f32 v[36:37], v[92:93], v[36:37]
	v_pk_mul_f32 v[40:41], v[92:93], v[40:41]
	v_pk_mul_f32 v[44:45], v[92:93], v[44:45]
	v_pk_mul_f32 v[64:65], v[92:93], v[64:65]
	v_pk_mul_f32 v[86:87], v[92:93], v[86:87]
	v_pk_mul_f32 v[90:91], v[92:93], v[90:91]
	v_pk_fma_f32 v[28:29], v[104:105], v[88:89], v[28:29] neg_lo:[0,0,1] neg_hi:[0,0,1]
	v_pk_fma_f32 v[26:27], v[88:89], v[26:27], v[32:33] neg_lo:[0,0,1] neg_hi:[0,0,1]
	v_pk_fma_f32 v[30:31], v[88:89], v[30:31], v[36:37] neg_lo:[0,0,1] neg_hi:[0,0,1]
	v_pk_fma_f32 v[32:33], v[88:89], v[34:35], v[40:41] neg_lo:[0,0,1] neg_hi:[0,0,1]
	v_pk_fma_f32 v[34:35], v[88:89], v[38:39], v[44:45] neg_lo:[0,0,1] neg_hi:[0,0,1]
	v_pk_fma_f32 v[36:37], v[88:89], v[42:43], v[64:65] neg_lo:[0,0,1] neg_hi:[0,0,1]
	v_pk_fma_f32 v[38:39], v[88:89], v[62:63], v[86:87] neg_lo:[0,0,1] neg_hi:[0,0,1]
	v_pk_fma_f32 v[40:41], v[88:89], v[84:85], v[90:91] neg_lo:[0,0,1] neg_hi:[0,0,1]
	s_cmp_eq_u32 s0, 64
	v_pk_add_f32 v[22:23], v[22:23], v[28:29]
	v_pk_add_f32 v[20:21], v[20:21], v[26:27]
	v_pk_add_f32 v[18:19], v[18:19], v[30:31]
	v_pk_add_f32 v[16:17], v[16:17], v[32:33]
	v_pk_add_f32 v[14:15], v[14:15], v[34:35]
	v_pk_add_f32 v[12:13], v[12:13], v[36:37]
	v_pk_add_f32 v[10:11], v[10:11], v[38:39]
	v_pk_add_f32 v[8:9], v[8:9], v[40:41]
	s_cbranch_scc0 .LBB0_138
	ds_bpermute_b32 v26, v46, v20
	ds_bpermute_b32 v27, v46, v21
	ds_bpermute_b32 v28, v46, v18
	ds_bpermute_b32 v29, v46, v19
	ds_bpermute_b32 v36, v46, v12
	ds_bpermute_b32 v37, v46, v13
	s_waitcnt lgkmcnt(4)
	v_pk_add_f32 v[26:27], v[20:21], v[26:27]
	ds_bpermute_b32 v30, v47, v26
	s_waitcnt lgkmcnt(3)
	v_pk_add_f32 v[28:29], v[18:19], v[28:29]
	ds_bpermute_b32 v31, v47, v27
	ds_bpermute_b32 v32, v47, v28
	ds_bpermute_b32 v33, v47, v29
	s_waitcnt lgkmcnt(4)
	v_pk_add_f32 v[12:13], v[12:13], v[36:37]
	ds_bpermute_b32 v24, v46, v22
	s_waitcnt lgkmcnt(3)
	v_pk_add_f32 v[18:19], v[26:27], v[30:31]
	ds_bpermute_b32 v30, v46, v16
	s_waitcnt lgkmcnt(2)
	v_pk_add_f32 v[26:27], v[28:29], v[32:33]
	ds_bpermute_b32 v31, v46, v17
	ds_bpermute_b32 v32, v46, v14
	ds_bpermute_b32 v33, v46, v15
	ds_bpermute_b32 v25, v46, v23
	ds_bpermute_b32 v38, v46, v10
	s_waitcnt lgkmcnt(4)
	v_pk_add_f32 v[16:17], v[16:17], v[30:31]
	ds_bpermute_b32 v30, v47, v16
	s_waitcnt lgkmcnt(3)
	v_pk_add_f32 v[32:33], v[14:15], v[32:33]
	ds_bpermute_b32 v31, v47, v17
	ds_bpermute_b32 v34, v47, v32
	ds_bpermute_b32 v35, v47, v33
	ds_bpermute_b32 v39, v46, v11
	s_waitcnt lgkmcnt(6)
	v_pk_add_f32 v[22:23], v[22:23], v[24:25]
	s_waitcnt lgkmcnt(3)
	v_pk_add_f32 v[14:15], v[16:17], v[30:31]
	ds_bpermute_b32 v24, v47, v22
	s_waitcnt lgkmcnt(2)
	v_pk_add_f32 v[16:17], v[32:33], v[34:35]
	ds_bpermute_b32 v34, v47, v12
	ds_bpermute_b32 v35, v47, v13
	s_waitcnt lgkmcnt(3)
	v_pk_add_f32 v[10:11], v[10:11], v[38:39]
	ds_bpermute_b32 v25, v47, v23
	ds_bpermute_b32 v38, v47, v10
	ds_bpermute_b32 v39, v47, v11
	s_waitcnt lgkmcnt(3)
	v_pk_add_f32 v[34:35], v[12:13], v[34:35]
	ds_bpermute_b32 v12, v46, v8
	ds_bpermute_b32 v13, v46, v9
	s_waitcnt lgkmcnt(4)
	v_pk_add_f32 v[20:21], v[22:23], v[24:25]
	s_waitcnt lgkmcnt(2)
	v_pk_add_f32 v[38:39], v[10:11], v[38:39]
	ds_bpermute_b32 v22, v48, v20
	ds_bpermute_b32 v23, v48, v21
	s_waitcnt lgkmcnt(2)
	v_pk_add_f32 v[8:9], v[8:9], v[12:13]
	ds_bpermute_b32 v12, v47, v8
	ds_bpermute_b32 v13, v47, v9
	ds_bpermute_b32 v24, v48, v18
	ds_bpermute_b32 v25, v48, v19
	ds_bpermute_b32 v28, v48, v26
	ds_bpermute_b32 v29, v48, v27
	s_waitcnt lgkmcnt(4)
	v_pk_add_f32 v[42:43], v[8:9], v[12:13]
	ds_bpermute_b32 v30, v48, v14
	ds_bpermute_b32 v31, v48, v15
	ds_bpermute_b32 v32, v48, v16
	ds_bpermute_b32 v33, v48, v17
	ds_bpermute_b32 v36, v48, v34
	ds_bpermute_b32 v37, v48, v35
	ds_bpermute_b32 v40, v48, v38
	ds_bpermute_b32 v41, v48, v39
	ds_bpermute_b32 v44, v48, v42
	ds_bpermute_b32 v45, v48, v43
	s_lshl_b32 s21, s18, 2
	s_and_saveexec_b64 s[0:1], s[6:7]
	s_cbranch_execz .LBB0_143
	v_add_u32_e32 v2, s21, v99
	v_pk_add_f32 v[8:9], v[20:21], v[22:23]
	s_waitcnt lgkmcnt(12)
	v_pk_add_f32 v[10:11], v[18:19], v[24:25]
	s_waitcnt lgkmcnt(10)
	v_pk_add_f32 v[12:13], v[26:27], v[28:29]
	s_waitcnt lgkmcnt(8)
	v_pk_add_f32 v[14:15], v[14:15], v[30:31]
	s_waitcnt lgkmcnt(6)
	v_pk_add_f32 v[16:17], v[16:17], v[32:33]
	s_waitcnt lgkmcnt(4)
	v_pk_add_f32 v[18:19], v[34:35], v[36:37]
	s_waitcnt lgkmcnt(2)
	v_pk_add_f32 v[20:21], v[38:39], v[40:41]
	s_waitcnt lgkmcnt(0)
	v_pk_add_f32 v[22:23], v[42:43], v[44:45]
	v_cmp_eq_u32_e32 vcc, v2, v100
	s_and_saveexec_b64 s[12:13], vcc
	s_cbranch_execz .LBB0_142
	v_readlane_b32 s36, v244, 2
	v_readlane_b32 s37, v244, 3
	v_readlane_b32 s38, v244, 4
	v_readlane_b32 s39, v244, 5
	v_readlane_b32 s40, v244, 6
	v_readlane_b32 s41, v244, 7
	v_readlane_b32 s42, v244, 8
	v_readlane_b32 s43, v244, 9
	v_readlane_b32 s44, v244, 10
	v_readlane_b32 s45, v244, 11
	v_readlane_b32 s46, v244, 12
	v_readlane_b32 s47, v244, 13
	v_readlane_b32 s48, v244, 14
	v_readlane_b32 s49, v244, 15
	v_readlane_b32 s50, v244, 16
	v_readlane_b32 s51, v244, 17
	s_waitcnt vmcnt(0)
	v_add_f32_e32 v8, v8, v124
